# in-proj epilogue: the 16 conditional sigmoid blocks re-emitted with packed c*x and +1 (v_pk_mul/v_pk_add), same arithmetic
# baseline (speedup 1.0000x reference)
; __device__ __forceinline__ unsigned cvt_pk_bf16(float lo, float hi) { unsigned r; asm volatile("v_cvt_pk_bf16_f32 %0, %1, %2" : "=v"(r) : "v"(lo), "v"(hi)); return r; }
; __device__ __forceinline__ float sigmoidf_(float v) { return __builtin_amdgcn_rcpf(1.0f + __builtin_amdgcn_exp2f(-1.4426950408889634f * v)); }
;     __device__ __forceinline__ void operator()(const f32x4 (&acc)[2][2][4][2], const Unit& u, int wr, int wc, int fr, int fq) const {
;         const int row0 = u.pm * BM + wr * 64 + fr, col0 = u.pn * BM + wc * 32 + 8 * fq;
;         const bool sig = (u.pn * BM >= ZO_GC);
;         float rs[2][4];
; #pragma unroll
;         for (int ai = 0; ai < 2; ++ai)
; #pragma unroll
;             for (int m = 0; m < 4; ++m) rs[ai][m] = ss[row0 + ai * HALF + m * 16];
;         __builtin_amdgcn_sched_barrier(0);
; #pragma unroll
;         for (int ai = 0; ai < 2; ++ai)
; #pragma unroll
;             for (int m = 0; m < 4; ++m) {
;                 const int row = row0 + ai * HALF + m * 16;
;                 const float r = __builtin_amdgcn_rsqf(rs[ai][m] * (1.0f / DM) + EPSN);
; #pragma unroll
;                 for (int bj = 0; bj < 2; ++bj) {
;                     f32x4 v0 = acc[ai][bj][m][0] * r, v1 = acc[ai][bj][m][1] * r;
;                     if (sig) {
; #pragma unroll
;                         for (int i = 0; i < 4; ++i) { v0[i] = sigmoidf_(v0[i]); v1[i] = sigmoidf_(v1[i]); }
;                     }
;                     u32x4 w; w.x = cvt_pk_bf16(v0[0], v0[1]); w.y = cvt_pk_bf16(v0[2], v0[3]); w.z = cvt_pk_bf16(v1[0], v1[1]); w.w = cvt_pk_bf16(v1[2], v1[3]);
;                     *(u32x4*)(z + (size_t)row * DIN + col0 + bj * HALF) = w;
;                 }
.LBB0_619:
	v_lshl_add_u32 v132, s36, 8, v144
	v_or_b32_e32 v138, 16, v132
	v_ashrrev_i32_e32 v133, 31, v132
	v_ashrrev_i32_e32 v139, 31, v138
	v_or_b32_e32 v136, 32, v132
	v_lshl_add_u64 v[140:141], v[132:133], 2, s[16:17]
	v_lshl_add_u64 v[134:135], v[138:139], 2, s[16:17]
	v_ashrrev_i32_e32 v137, 31, v136
	global_load_dword v154, v[140:141], off
	global_load_dword v153, v[134:135], off
	v_lshl_add_u64 v[134:135], v[136:137], 2, s[16:17]
	global_load_dword v152, v[134:135], off
	v_or_b32_e32 v134, 48, v132
	v_ashrrev_i32_e32 v135, 31, v134
	v_lshl_add_u64 v[142:143], v[134:135], 2, s[16:17]
	global_load_dword v151, v[142:143], off
	global_load_dword v139, v[140:141], off offset:512
	global_load_dword v137, v[140:141], off offset:576
	global_load_dword v135, v[140:141], off offset:640
	global_load_dword v133, v[140:141], off offset:704
	s_cmp_gt_i32 s0, 17
	s_cselect_b64 s[36:37], -1, 0
	s_cmp_lt_i32 s0, 18
	s_waitcnt vmcnt(0)
	s_mov_b32 s100, 0xbfb8aa3b
	s_mov_b32 s101, 0xbfb8aa3b
	v_fmamk_f32 v140, v154, 0x3a000000, v150
	v_rsq_f32_e32 v140, v140
	s_nop 0
	v_pk_mul_f32 v[126:127], v[126:127], v[140:141] op_sel_hi:[1,0]
	v_pk_mul_f32 v[124:125], v[124:125], v[140:141] op_sel_hi:[1,0]
	v_pk_mul_f32 v[122:123], v[122:123], v[140:141] op_sel_hi:[1,0]
	v_pk_mul_f32 v[142:143], v[120:121], v[140:141] op_sel_hi:[1,0]
	s_cbranch_scc1 .LBB0_621
	v_pk_mul_f32 v[156:157], v[122:123], s[100:101]
	v_pk_mul_f32 v[158:159], v[124:125], s[100:101]
	v_exp_f32_e32 v156, v156
	v_exp_f32_e32 v157, v157
	v_exp_f32_e32 v158, v158
	v_exp_f32_e32 v159, v159
	v_pk_add_f32 v[156:157], v[156:157], 1.0 op_sel_hi:[1,0]
	v_pk_add_f32 v[158:159], v[158:159], 1.0 op_sel_hi:[1,0]
	v_rcp_f32_e32 v122, v156
	v_rcp_f32_e32 v123, v157
	v_rcp_f32_e32 v124, v158
	v_rcp_f32_e32 v125, v159
	v_pk_mul_f32 v[156:157], v[126:127], s[100:101]
	v_pk_mul_f32 v[158:159], v[142:143], s[100:101]
	v_exp_f32_e32 v156, v156
	v_exp_f32_e32 v157, v157
	v_exp_f32_e32 v158, v158
	v_exp_f32_e32 v159, v159
	v_pk_add_f32 v[156:157], v[156:157], 1.0 op_sel_hi:[1,0]
	v_pk_add_f32 v[158:159], v[158:159], 1.0 op_sel_hi:[1,0]
	v_rcp_f32_e32 v126, v156
	v_rcp_f32_e32 v127, v157
	v_rcp_f32_e32 v142, v158
	v_rcp_f32_e32 v143, v159
	s_nop 0
.LBB0_621:
	v_lshl_or_b32 v120, s0, 8, v146
	v_cvt_pk_bf16_f32 v124, v124, v125
	v_cvt_pk_bf16_f32 v125, v126, v127
	v_cvt_pk_bf16_f32 v126, v142, v143
	v_cvt_pk_bf16_f32 v127, v122, v123
	v_mov_b64_e32 v[122:123], s[4:5]
	v_ashrrev_i32_e32 v121, 31, v120
	v_mad_i64_i32 v[122:123], s[0:1], v132, s52, v[122:123]
	v_lshl_add_u64 v[122:123], v[120:121], 1, v[122:123]
	global_store_dwordx4 v[122:123], v[124:127], off
	v_mov_b32_e32 v141, v140
	v_pk_mul_f32 v[116:117], v[116:117], v[140:141]
	v_mov_b32_e32 v124, v140
	v_mov_b32_e32 v125, v140
	v_pk_mul_f32 v[118:119], v[118:119], v[124:125]
	v_pk_mul_f32 v[114:115], v[114:115], v[124:125]
	v_cndmask_b32_e64 v124, 0, 1, s[36:37]
	v_cmp_ne_u32_e64 s[0:1], 1, v124
	s_andn2_b64 vcc, exec, s[36:37]
	v_pk_mul_f32 v[112:113], v[112:113], v[140:141]
	s_cbranch_vccnz .LBB0_623
	v_pk_mul_f32 v[156:157], v[112:113], s[100:101]
	v_pk_mul_f32 v[158:159], v[114:115], s[100:101]
	v_exp_f32_e32 v156, v156
	v_exp_f32_e32 v157, v157
	v_exp_f32_e32 v158, v158
	v_exp_f32_e32 v159, v159
	v_pk_add_f32 v[156:157], v[156:157], 1.0 op_sel_hi:[1,0]
	v_pk_add_f32 v[158:159], v[158:159], 1.0 op_sel_hi:[1,0]
	v_rcp_f32_e32 v112, v156
	v_rcp_f32_e32 v113, v157
	v_rcp_f32_e32 v114, v158
	v_rcp_f32_e32 v115, v159
	v_pk_mul_f32 v[156:157], v[116:117], s[100:101]
	v_pk_mul_f32 v[158:159], v[118:119], s[100:101]
	v_exp_f32_e32 v156, v156
	v_exp_f32_e32 v157, v157
	v_exp_f32_e32 v158, v158
	v_exp_f32_e32 v159, v159
	v_pk_add_f32 v[156:157], v[156:157], 1.0 op_sel_hi:[1,0]
	v_pk_add_f32 v[158:159], v[158:159], 1.0 op_sel_hi:[1,0]
	v_rcp_f32_e32 v116, v156
	v_rcp_f32_e32 v117, v157
	v_rcp_f32_e32 v118, v158
	v_rcp_f32_e32 v119, v159
	s_nop 0
.LBB0_623:
	v_cvt_pk_bf16_f32 v116, v116, v117
	v_cvt_pk_bf16_f32 v117, v118, v119
	v_cvt_pk_bf16_f32 v118, v112, v113
	v_cvt_pk_bf16_f32 v119, v114, v115
	global_store_dwordx4 v[122:123], v[116:119], off offset:256
	v_fmamk_f32 v112, v153, 0x3a000000, v150
	v_rsq_f32_e32 v112, v112
	s_and_b64 vcc, exec, s[0:1]
	v_pk_mul_f32 v[110:111], v[110:111], v[112:113] op_sel_hi:[1,0]
	v_pk_mul_f32 v[108:109], v[108:109], v[112:113] op_sel_hi:[1,0]
	v_pk_mul_f32 v[106:107], v[106:107], v[112:113] op_sel_hi:[1,0]
	v_pk_mul_f32 v[104:105], v[104:105], v[112:113] op_sel_hi:[1,0]
	s_cbranch_vccnz .LBB0_625
	v_pk_mul_f32 v[156:157], v[104:105], s[100:101]
	v_pk_mul_f32 v[158:159], v[106:107], s[100:101]
	v_exp_f32_e32 v156, v156
	v_exp_f32_e32 v157, v157
	v_exp_f32_e32 v158, v158
	v_exp_f32_e32 v159, v159
	v_pk_add_f32 v[156:157], v[156:157], 1.0 op_sel_hi:[1,0]
	v_pk_add_f32 v[158:159], v[158:159], 1.0 op_sel_hi:[1,0]
	v_rcp_f32_e32 v104, v156
	v_rcp_f32_e32 v105, v157
	v_rcp_f32_e32 v106, v158
	v_rcp_f32_e32 v107, v159
	v_pk_mul_f32 v[156:157], v[108:109], s[100:101]
	v_pk_mul_f32 v[158:159], v[110:111], s[100:101]
	v_exp_f32_e32 v156, v156
	v_exp_f32_e32 v157, v157
	v_exp_f32_e32 v158, v158
	v_exp_f32_e32 v159, v159
	v_pk_add_f32 v[156:157], v[156:157], 1.0 op_sel_hi:[1,0]
	v_pk_add_f32 v[158:159], v[158:159], 1.0 op_sel_hi:[1,0]
	v_rcp_f32_e32 v108, v156
	v_rcp_f32_e32 v109, v157
	v_rcp_f32_e32 v110, v158
	v_rcp_f32_e32 v111, v159
	s_nop 0
; __device__ __forceinline__ unsigned cvt_pk_bf16(float lo, float hi) { unsigned r; asm volatile("v_cvt_pk_bf16_f32 %0, %1, %2" : "=v"(r) : "v"(lo), "v"(hi)); return r; }
; __device__ __forceinline__ float sigmoidf_(float v) { return __builtin_amdgcn_rcpf(1.0f + __builtin_amdgcn_exp2f(-1.4426950408889634f * v)); }
;     __device__ __forceinline__ void operator()(const f32x4 (&acc)[2][2][4][2], const Unit& u, int wr, int wc, int fr, int fq) const {
;     ...
;             for (int m = 0; m < 4; ++m) {
;                 const int row = row0 + ai * HALF + m * 16;
;                 const float r = __builtin_amdgcn_rsqf(rs[ai][m] * (1.0f / DM) + EPSN);
; #pragma unroll
;                 for (int bj = 0; bj < 2; ++bj) {
;                     f32x4 v0 = acc[ai][bj][m][0] * r, v1 = acc[ai][bj][m][1] * r;
;                     if (sig) {
; #pragma unroll
;                         for (int i = 0; i < 4; ++i) { v0[i] = sigmoidf_(v0[i]); v1[i] = sigmoidf_(v1[i]); }
;                     }
;                     u32x4 w; w.x = cvt_pk_bf16(v0[0], v0[1]); w.y = cvt_pk_bf16(v0[2], v0[3]); w.z = cvt_pk_bf16(v1[0], v1[1]); w.w = cvt_pk_bf16(v1[2], v1[3]);
;                     *(u32x4*)(z + (size_t)row * DIN + col0 + bj * HALF) = w;
;                 }
.LBB0_625:
	v_cvt_pk_bf16_f32 v108, v108, v109
	v_cvt_pk_bf16_f32 v109, v110, v111
	v_cvt_pk_bf16_f32 v110, v104, v105
	v_mov_b64_e32 v[104:105], s[4:5]
	v_mov_b32_e32 v113, v112
	v_cvt_pk_bf16_f32 v111, v106, v107
	v_mad_i64_i32 v[104:105], s[36:37], v138, s52, v[104:105]
	v_mov_b32_e32 v106, v112
	v_mov_b32_e32 v107, v112
	v_lshl_add_u64 v[104:105], v[120:121], 1, v[104:105]
	v_pk_mul_f32 v[102:103], v[102:103], v[106:107]
	v_pk_mul_f32 v[100:101], v[100:101], v[112:113]
	v_pk_mul_f32 v[98:99], v[98:99], v[106:107]
	s_and_b64 vcc, exec, s[0:1]
	v_pk_mul_f32 v[96:97], v[96:97], v[112:113]
	global_store_dwordx4 v[104:105], v[108:111], off
	s_cbranch_vccnz .LBB0_627
	v_pk_mul_f32 v[156:157], v[96:97], s[100:101]
	v_pk_mul_f32 v[158:159], v[98:99], s[100:101]
	v_exp_f32_e32 v156, v156
	v_exp_f32_e32 v157, v157
	v_exp_f32_e32 v158, v158
	v_exp_f32_e32 v159, v159
	v_pk_add_f32 v[156:157], v[156:157], 1.0 op_sel_hi:[1,0]
	v_pk_add_f32 v[158:159], v[158:159], 1.0 op_sel_hi:[1,0]
	v_rcp_f32_e32 v96, v156
	v_rcp_f32_e32 v97, v157
	v_rcp_f32_e32 v98, v158
	v_rcp_f32_e32 v99, v159
	v_pk_mul_f32 v[156:157], v[100:101], s[100:101]
	v_pk_mul_f32 v[158:159], v[102:103], s[100:101]
	v_exp_f32_e32 v156, v156
	v_exp_f32_e32 v157, v157
	v_exp_f32_e32 v158, v158
	v_exp_f32_e32 v159, v159
	v_pk_add_f32 v[156:157], v[156:157], 1.0 op_sel_hi:[1,0]
	v_pk_add_f32 v[158:159], v[158:159], 1.0 op_sel_hi:[1,0]
	v_rcp_f32_e32 v100, v156
	v_rcp_f32_e32 v101, v157
	v_rcp_f32_e32 v102, v158
	v_rcp_f32_e32 v103, v159
	s_nop 0
.LBB0_627:
	v_cvt_pk_bf16_f32 v100, v100, v101
	v_cvt_pk_bf16_f32 v101, v102, v103
	v_cvt_pk_bf16_f32 v102, v96, v97
	v_cvt_pk_bf16_f32 v103, v98, v99
	global_store_dwordx4 v[104:105], v[100:103], off offset:256
	v_fmamk_f32 v96, v152, 0x3a000000, v150
	v_rsq_f32_e32 v96, v96
	s_and_b64 vcc, exec, s[0:1]
	v_pk_mul_f32 v[94:95], v[94:95], v[96:97] op_sel_hi:[1,0]
	v_pk_mul_f32 v[92:93], v[92:93], v[96:97] op_sel_hi:[1,0]
	v_pk_mul_f32 v[90:91], v[90:91], v[96:97] op_sel_hi:[1,0]
	v_pk_mul_f32 v[88:89], v[88:89], v[96:97] op_sel_hi:[1,0]
	s_cbranch_vccnz .LBB0_629
	v_pk_mul_f32 v[156:157], v[88:89], s[100:101]
	v_pk_mul_f32 v[158:159], v[90:91], s[100:101]
	v_exp_f32_e32 v156, v156
	v_exp_f32_e32 v157, v157
	v_exp_f32_e32 v158, v158
	v_exp_f32_e32 v159, v159
	v_pk_add_f32 v[156:157], v[156:157], 1.0 op_sel_hi:[1,0]
	v_pk_add_f32 v[158:159], v[158:159], 1.0 op_sel_hi:[1,0]
	v_rcp_f32_e32 v88, v156
	v_rcp_f32_e32 v89, v157
	v_rcp_f32_e32 v90, v158
	v_rcp_f32_e32 v91, v159
	v_pk_mul_f32 v[156:157], v[92:93], s[100:101]
	v_pk_mul_f32 v[158:159], v[94:95], s[100:101]
	v_exp_f32_e32 v156, v156
	v_exp_f32_e32 v157, v157
	v_exp_f32_e32 v158, v158
	v_exp_f32_e32 v159, v159
	v_pk_add_f32 v[156:157], v[156:157], 1.0 op_sel_hi:[1,0]
	v_pk_add_f32 v[158:159], v[158:159], 1.0 op_sel_hi:[1,0]
	v_rcp_f32_e32 v92, v156
	v_rcp_f32_e32 v93, v157
	v_rcp_f32_e32 v94, v158
	v_rcp_f32_e32 v95, v159
	s_nop 0
.LBB0_629:
	v_cvt_pk_bf16_f32 v92, v92, v93
	v_cvt_pk_bf16_f32 v93, v94, v95
	v_cvt_pk_bf16_f32 v94, v88, v89
	v_mov_b64_e32 v[88:89], s[4:5]
	v_mov_b32_e32 v97, v96
	v_cvt_pk_bf16_f32 v95, v90, v91
	v_mad_i64_i32 v[88:89], s[36:37], v136, s52, v[88:89]
	v_mov_b32_e32 v90, v96
	v_mov_b32_e32 v91, v96
	v_lshl_add_u64 v[88:89], v[120:121], 1, v[88:89]
	v_pk_mul_f32 v[86:87], v[86:87], v[90:91]
	v_pk_mul_f32 v[84:85], v[84:85], v[96:97]
	v_pk_mul_f32 v[82:83], v[82:83], v[90:91]
	s_and_b64 vcc, exec, s[0:1]
	v_pk_mul_f32 v[80:81], v[80:81], v[96:97]
	global_store_dwordx4 v[88:89], v[92:95], off
	s_cbranch_vccnz .LBB0_631
	v_pk_mul_f32 v[156:157], v[80:81], s[100:101]
	v_pk_mul_f32 v[158:159], v[82:83], s[100:101]
	v_exp_f32_e32 v156, v156
	v_exp_f32_e32 v157, v157
	v_exp_f32_e32 v158, v158
	v_exp_f32_e32 v159, v159
	v_pk_add_f32 v[156:157], v[156:157], 1.0 op_sel_hi:[1,0]
	v_pk_add_f32 v[158:159], v[158:159], 1.0 op_sel_hi:[1,0]
	v_rcp_f32_e32 v80, v156
	v_rcp_f32_e32 v81, v157
	v_rcp_f32_e32 v82, v158
	v_rcp_f32_e32 v83, v159
	v_pk_mul_f32 v[156:157], v[84:85], s[100:101]
	v_pk_mul_f32 v[158:159], v[86:87], s[100:101]
	v_exp_f32_e32 v156, v156
	v_exp_f32_e32 v157, v157
	v_exp_f32_e32 v158, v158
	v_exp_f32_e32 v159, v159
	v_pk_add_f32 v[156:157], v[156:157], 1.0 op_sel_hi:[1,0]
	v_pk_add_f32 v[158:159], v[158:159], 1.0 op_sel_hi:[1,0]
	v_rcp_f32_e32 v84, v156
	v_rcp_f32_e32 v85, v157
	v_rcp_f32_e32 v86, v158
	v_rcp_f32_e32 v87, v159
	s_nop 0
.LBB0_631:
	v_cvt_pk_bf16_f32 v84, v84, v85
	v_cvt_pk_bf16_f32 v85, v86, v87
	v_cvt_pk_bf16_f32 v86, v80, v81
	v_cvt_pk_bf16_f32 v87, v82, v83
	global_store_dwordx4 v[88:89], v[84:87], off offset:256
	v_fmamk_f32 v80, v151, 0x3a000000, v150
	v_rsq_f32_e32 v80, v80
	s_and_b64 vcc, exec, s[0:1]
	v_pk_mul_f32 v[78:79], v[78:79], v[80:81] op_sel_hi:[1,0]
	v_pk_mul_f32 v[76:77], v[76:77], v[80:81] op_sel_hi:[1,0]
	v_pk_mul_f32 v[74:75], v[74:75], v[80:81] op_sel_hi:[1,0]
	v_pk_mul_f32 v[72:73], v[72:73], v[80:81] op_sel_hi:[1,0]
	s_cbranch_vccnz .LBB0_633
	v_pk_mul_f32 v[156:157], v[72:73], s[100:101]
	v_pk_mul_f32 v[158:159], v[74:75], s[100:101]
	v_exp_f32_e32 v156, v156
	v_exp_f32_e32 v157, v157
	v_exp_f32_e32 v158, v158
	v_exp_f32_e32 v159, v159
	v_pk_add_f32 v[156:157], v[156:157], 1.0 op_sel_hi:[1,0]
	v_pk_add_f32 v[158:159], v[158:159], 1.0 op_sel_hi:[1,0]
	v_rcp_f32_e32 v72, v156
	v_rcp_f32_e32 v73, v157
	v_rcp_f32_e32 v74, v158
	v_rcp_f32_e32 v75, v159
	v_pk_mul_f32 v[156:157], v[76:77], s[100:101]
	v_pk_mul_f32 v[158:159], v[78:79], s[100:101]
	v_exp_f32_e32 v156, v156
	v_exp_f32_e32 v157, v157
	v_exp_f32_e32 v158, v158
	v_exp_f32_e32 v159, v159
	v_pk_add_f32 v[156:157], v[156:157], 1.0 op_sel_hi:[1,0]
	v_pk_add_f32 v[158:159], v[158:159], 1.0 op_sel_hi:[1,0]
	v_rcp_f32_e32 v76, v156
	v_rcp_f32_e32 v77, v157
	v_rcp_f32_e32 v78, v158
	v_rcp_f32_e32 v79, v159
	s_nop 0
; __device__ __forceinline__ unsigned cvt_pk_bf16(float lo, float hi) { unsigned r; asm volatile("v_cvt_pk_bf16_f32 %0, %1, %2" : "=v"(r) : "v"(lo), "v"(hi)); return r; }
; __device__ __forceinline__ float sigmoidf_(float v) { return __builtin_amdgcn_rcpf(1.0f + __builtin_amdgcn_exp2f(-1.4426950408889634f * v)); }
;     __device__ __forceinline__ void operator()(const f32x4 (&acc)[2][2][4][2], const Unit& u, int wr, int wc, int fr, int fq) const {
;     ...
;             for (int m = 0; m < 4; ++m) {
;                 const int row = row0 + ai * HALF + m * 16;
;                 const float r = __builtin_amdgcn_rsqf(rs[ai][m] * (1.0f / DM) + EPSN);
; #pragma unroll
;                 for (int bj = 0; bj < 2; ++bj) {
;                     f32x4 v0 = acc[ai][bj][m][0] * r, v1 = acc[ai][bj][m][1] * r;
;                     if (sig) {
; #pragma unroll
;                         for (int i = 0; i < 4; ++i) { v0[i] = sigmoidf_(v0[i]); v1[i] = sigmoidf_(v1[i]); }
;                     }
;                     u32x4 w; w.x = cvt_pk_bf16(v0[0], v0[1]); w.y = cvt_pk_bf16(v0[2], v0[3]); w.z = cvt_pk_bf16(v1[0], v1[1]); w.w = cvt_pk_bf16(v1[2], v1[3]);
;                     *(u32x4*)(z + (size_t)row * DIN + col0 + bj * HALF) = w;
;                 }
.LBB0_633:
	v_cvt_pk_bf16_f32 v76, v76, v77
	v_cvt_pk_bf16_f32 v77, v78, v79
	v_cvt_pk_bf16_f32 v78, v72, v73
	v_mov_b64_e32 v[72:73], s[4:5]
	v_mov_b32_e32 v81, v80
	v_cvt_pk_bf16_f32 v79, v74, v75
	v_mad_i64_i32 v[72:73], s[36:37], v134, s52, v[72:73]
	v_mov_b32_e32 v74, v80
	v_mov_b32_e32 v75, v80
	v_lshl_add_u64 v[72:73], v[120:121], 1, v[72:73]
	v_pk_mul_f32 v[70:71], v[70:71], v[74:75]
	v_pk_mul_f32 v[68:69], v[68:69], v[80:81]
	v_pk_mul_f32 v[66:67], v[66:67], v[74:75]
	s_and_b64 vcc, exec, s[0:1]
	v_pk_mul_f32 v[64:65], v[64:65], v[80:81]
	global_store_dwordx4 v[72:73], v[76:79], off
	s_cbranch_vccnz .LBB0_635
	v_pk_mul_f32 v[156:157], v[64:65], s[100:101]
	v_pk_mul_f32 v[158:159], v[66:67], s[100:101]
	v_exp_f32_e32 v156, v156
	v_exp_f32_e32 v157, v157
	v_exp_f32_e32 v158, v158
	v_exp_f32_e32 v159, v159
	v_pk_add_f32 v[156:157], v[156:157], 1.0 op_sel_hi:[1,0]
	v_pk_add_f32 v[158:159], v[158:159], 1.0 op_sel_hi:[1,0]
	v_rcp_f32_e32 v64, v156
	v_rcp_f32_e32 v65, v157
	v_rcp_f32_e32 v66, v158
	v_rcp_f32_e32 v67, v159
	v_pk_mul_f32 v[156:157], v[68:69], s[100:101]
	v_pk_mul_f32 v[158:159], v[70:71], s[100:101]
	v_exp_f32_e32 v156, v156
	v_exp_f32_e32 v157, v157
	v_exp_f32_e32 v158, v158
	v_exp_f32_e32 v159, v159
	v_pk_add_f32 v[156:157], v[156:157], 1.0 op_sel_hi:[1,0]
	v_pk_add_f32 v[158:159], v[158:159], 1.0 op_sel_hi:[1,0]
	v_rcp_f32_e32 v68, v156
	v_rcp_f32_e32 v69, v157
	v_rcp_f32_e32 v70, v158
	v_rcp_f32_e32 v71, v159
	s_nop 0
.LBB0_635:
	v_cvt_pk_bf16_f32 v68, v68, v69
	v_cvt_pk_bf16_f32 v69, v70, v71
	v_cvt_pk_bf16_f32 v70, v64, v65
	v_cvt_pk_bf16_f32 v71, v66, v67
	global_store_dwordx4 v[72:73], v[68:71], off offset:256
	v_fmamk_f32 v64, v139, 0x3a000000, v150
	v_rsq_f32_e32 v64, v64
	s_and_b64 vcc, exec, s[0:1]
	v_pk_mul_f32 v[62:63], v[62:63], v[64:65] op_sel_hi:[1,0]
	v_pk_mul_f32 v[60:61], v[60:61], v[64:65] op_sel_hi:[1,0]
	v_pk_mul_f32 v[58:59], v[58:59], v[64:65] op_sel_hi:[1,0]
	v_pk_mul_f32 v[56:57], v[56:57], v[64:65] op_sel_hi:[1,0]
	s_cbranch_vccnz .LBB0_637
	v_pk_mul_f32 v[156:157], v[56:57], s[100:101]
	v_pk_mul_f32 v[158:159], v[58:59], s[100:101]
	v_exp_f32_e32 v156, v156
	v_exp_f32_e32 v157, v157
	v_exp_f32_e32 v158, v158
	v_exp_f32_e32 v159, v159
	v_pk_add_f32 v[156:157], v[156:157], 1.0 op_sel_hi:[1,0]
	v_pk_add_f32 v[158:159], v[158:159], 1.0 op_sel_hi:[1,0]
	v_rcp_f32_e32 v56, v156
	v_rcp_f32_e32 v57, v157
	v_rcp_f32_e32 v58, v158
	v_rcp_f32_e32 v59, v159
	v_pk_mul_f32 v[156:157], v[60:61], s[100:101]
	v_pk_mul_f32 v[158:159], v[62:63], s[100:101]
	v_exp_f32_e32 v156, v156
	v_exp_f32_e32 v157, v157
	v_exp_f32_e32 v158, v158
	v_exp_f32_e32 v159, v159
	v_pk_add_f32 v[156:157], v[156:157], 1.0 op_sel_hi:[1,0]
	v_pk_add_f32 v[158:159], v[158:159], 1.0 op_sel_hi:[1,0]
	v_rcp_f32_e32 v60, v156
	v_rcp_f32_e32 v61, v157
	v_rcp_f32_e32 v62, v158
	v_rcp_f32_e32 v63, v159
	s_nop 0
.LBB0_637:
	v_add_u32_e32 v66, 0x80, v132
	v_cvt_pk_bf16_f32 v60, v60, v61
	v_cvt_pk_bf16_f32 v61, v62, v63
	v_cvt_pk_bf16_f32 v62, v56, v57
	v_mov_b64_e32 v[56:57], s[4:5]
	v_mov_b32_e32 v65, v64
	v_cvt_pk_bf16_f32 v63, v58, v59
	v_mad_i64_i32 v[56:57], s[36:37], v66, s52, v[56:57]
	v_mov_b32_e32 v58, v64
	v_mov_b32_e32 v59, v64
	v_lshl_add_u64 v[56:57], v[120:121], 1, v[56:57]
	v_pk_mul_f32 v[54:55], v[54:55], v[58:59]
	v_pk_mul_f32 v[52:53], v[52:53], v[64:65]
	v_pk_mul_f32 v[50:51], v[50:51], v[58:59]
	s_and_b64 vcc, exec, s[0:1]
	v_pk_mul_f32 v[48:49], v[48:49], v[64:65]
	global_store_dwordx4 v[56:57], v[60:63], off
	s_cbranch_vccnz .LBB0_639
	v_pk_mul_f32 v[156:157], v[48:49], s[100:101]
	v_pk_mul_f32 v[158:159], v[50:51], s[100:101]
	v_exp_f32_e32 v156, v156
	v_exp_f32_e32 v157, v157
	v_exp_f32_e32 v158, v158
	v_exp_f32_e32 v159, v159
	v_pk_add_f32 v[156:157], v[156:157], 1.0 op_sel_hi:[1,0]
	v_pk_add_f32 v[158:159], v[158:159], 1.0 op_sel_hi:[1,0]
	v_rcp_f32_e32 v48, v156
	v_rcp_f32_e32 v49, v157
	v_rcp_f32_e32 v50, v158
	v_rcp_f32_e32 v51, v159
	v_pk_mul_f32 v[156:157], v[52:53], s[100:101]
	v_pk_mul_f32 v[158:159], v[54:55], s[100:101]
	v_exp_f32_e32 v156, v156
	v_exp_f32_e32 v157, v157
	v_exp_f32_e32 v158, v158
	v_exp_f32_e32 v159, v159
	v_pk_add_f32 v[156:157], v[156:157], 1.0 op_sel_hi:[1,0]
	v_pk_add_f32 v[158:159], v[158:159], 1.0 op_sel_hi:[1,0]
	v_rcp_f32_e32 v52, v156
	v_rcp_f32_e32 v53, v157
	v_rcp_f32_e32 v54, v158
	v_rcp_f32_e32 v55, v159
	s_nop 0
.LBB0_639:
	v_cvt_pk_bf16_f32 v52, v52, v53
	v_cvt_pk_bf16_f32 v53, v54, v55
	v_cvt_pk_bf16_f32 v54, v48, v49
	v_cvt_pk_bf16_f32 v55, v50, v51
	global_store_dwordx4 v[56:57], v[52:55], off offset:256
	v_fmamk_f32 v48, v137, 0x3a000000, v150
	v_rsq_f32_e32 v48, v48
	s_and_b64 vcc, exec, s[0:1]
	v_pk_mul_f32 v[46:47], v[46:47], v[48:49] op_sel_hi:[1,0]
	v_pk_mul_f32 v[44:45], v[44:45], v[48:49] op_sel_hi:[1,0]
	v_pk_mul_f32 v[42:43], v[42:43], v[48:49] op_sel_hi:[1,0]
	v_pk_mul_f32 v[40:41], v[40:41], v[48:49] op_sel_hi:[1,0]
	s_cbranch_vccnz .LBB0_641
	v_pk_mul_f32 v[156:157], v[40:41], s[100:101]
	v_pk_mul_f32 v[158:159], v[42:43], s[100:101]
	v_exp_f32_e32 v156, v156
	v_exp_f32_e32 v157, v157
	v_exp_f32_e32 v158, v158
	v_exp_f32_e32 v159, v159
	v_pk_add_f32 v[156:157], v[156:157], 1.0 op_sel_hi:[1,0]
	v_pk_add_f32 v[158:159], v[158:159], 1.0 op_sel_hi:[1,0]
	v_rcp_f32_e32 v40, v156
	v_rcp_f32_e32 v41, v157
	v_rcp_f32_e32 v42, v158
	v_rcp_f32_e32 v43, v159
	v_pk_mul_f32 v[156:157], v[44:45], s[100:101]
	v_pk_mul_f32 v[158:159], v[46:47], s[100:101]
	v_exp_f32_e32 v156, v156
	v_exp_f32_e32 v157, v157
	v_exp_f32_e32 v158, v158
	v_exp_f32_e32 v159, v159
	v_pk_add_f32 v[156:157], v[156:157], 1.0 op_sel_hi:[1,0]
	v_pk_add_f32 v[158:159], v[158:159], 1.0 op_sel_hi:[1,0]
	v_rcp_f32_e32 v44, v156
	v_rcp_f32_e32 v45, v157
	v_rcp_f32_e32 v46, v158
	v_rcp_f32_e32 v47, v159
	s_nop 0
; __device__ __forceinline__ unsigned cvt_pk_bf16(float lo, float hi) { unsigned r; asm volatile("v_cvt_pk_bf16_f32 %0, %1, %2" : "=v"(r) : "v"(lo), "v"(hi)); return r; }
; __device__ __forceinline__ float sigmoidf_(float v) { return __builtin_amdgcn_rcpf(1.0f + __builtin_amdgcn_exp2f(-1.4426950408889634f * v)); }
;     __device__ __forceinline__ void operator()(const f32x4 (&acc)[2][2][4][2], const Unit& u, int wr, int wc, int fr, int fq) const {
;     ...
;             for (int m = 0; m < 4; ++m) {
;                 const int row = row0 + ai * HALF + m * 16;
;                 const float r = __builtin_amdgcn_rsqf(rs[ai][m] * (1.0f / DM) + EPSN);
; #pragma unroll
;                 for (int bj = 0; bj < 2; ++bj) {
;                     f32x4 v0 = acc[ai][bj][m][0] * r, v1 = acc[ai][bj][m][1] * r;
;                     if (sig) {
; #pragma unroll
;                         for (int i = 0; i < 4; ++i) { v0[i] = sigmoidf_(v0[i]); v1[i] = sigmoidf_(v1[i]); }
;                     }
;                     u32x4 w; w.x = cvt_pk_bf16(v0[0], v0[1]); w.y = cvt_pk_bf16(v0[2], v0[3]); w.z = cvt_pk_bf16(v1[0], v1[1]); w.w = cvt_pk_bf16(v1[2], v1[3]);
;                     *(u32x4*)(z + (size_t)row * DIN + col0 + bj * HALF) = w;
;                 }
.LBB0_641:
	v_add_u32_e32 v50, 0x90, v132
	v_cvt_pk_bf16_f32 v44, v44, v45
	v_cvt_pk_bf16_f32 v45, v46, v47
	v_cvt_pk_bf16_f32 v46, v40, v41
	v_mov_b64_e32 v[40:41], s[4:5]
	v_mov_b32_e32 v49, v48
	v_cvt_pk_bf16_f32 v47, v42, v43
	v_mad_i64_i32 v[40:41], s[36:37], v50, s52, v[40:41]
	v_mov_b32_e32 v42, v48
	v_mov_b32_e32 v43, v48
	v_lshl_add_u64 v[40:41], v[120:121], 1, v[40:41]
	v_pk_mul_f32 v[38:39], v[38:39], v[42:43]
	v_pk_mul_f32 v[36:37], v[36:37], v[48:49]
	v_pk_mul_f32 v[34:35], v[34:35], v[42:43]
	s_and_b64 vcc, exec, s[0:1]
	v_pk_mul_f32 v[32:33], v[32:33], v[48:49]
	global_store_dwordx4 v[40:41], v[44:47], off
	s_cbranch_vccnz .LBB0_643
	v_pk_mul_f32 v[156:157], v[32:33], s[100:101]
	v_pk_mul_f32 v[158:159], v[34:35], s[100:101]
	v_exp_f32_e32 v156, v156
	v_exp_f32_e32 v157, v157
	v_exp_f32_e32 v158, v158
	v_exp_f32_e32 v159, v159
	v_pk_add_f32 v[156:157], v[156:157], 1.0 op_sel_hi:[1,0]
	v_pk_add_f32 v[158:159], v[158:159], 1.0 op_sel_hi:[1,0]
	v_rcp_f32_e32 v32, v156
	v_rcp_f32_e32 v33, v157
	v_rcp_f32_e32 v34, v158
	v_rcp_f32_e32 v35, v159
	v_pk_mul_f32 v[156:157], v[36:37], s[100:101]
	v_pk_mul_f32 v[158:159], v[38:39], s[100:101]
	v_exp_f32_e32 v156, v156
	v_exp_f32_e32 v157, v157
	v_exp_f32_e32 v158, v158
	v_exp_f32_e32 v159, v159
	v_pk_add_f32 v[156:157], v[156:157], 1.0 op_sel_hi:[1,0]
	v_pk_add_f32 v[158:159], v[158:159], 1.0 op_sel_hi:[1,0]
	v_rcp_f32_e32 v36, v156
	v_rcp_f32_e32 v37, v157
	v_rcp_f32_e32 v38, v158
	v_rcp_f32_e32 v39, v159
	s_nop 0
.LBB0_643:
	v_cvt_pk_bf16_f32 v36, v36, v37
	v_cvt_pk_bf16_f32 v37, v38, v39
	v_cvt_pk_bf16_f32 v38, v32, v33
	v_cvt_pk_bf16_f32 v39, v34, v35
	global_store_dwordx4 v[40:41], v[36:39], off offset:256
	v_fmamk_f32 v32, v135, 0x3a000000, v150
	v_rsq_f32_e32 v32, v32
	s_and_b64 vcc, exec, s[0:1]
	v_pk_mul_f32 v[30:31], v[30:31], v[32:33] op_sel_hi:[1,0]
	v_pk_mul_f32 v[28:29], v[28:29], v[32:33] op_sel_hi:[1,0]
	v_pk_mul_f32 v[26:27], v[26:27], v[32:33] op_sel_hi:[1,0]
	v_pk_mul_f32 v[24:25], v[24:25], v[32:33] op_sel_hi:[1,0]
	s_cbranch_vccnz .LBB0_645
	v_pk_mul_f32 v[156:157], v[24:25], s[100:101]
	v_pk_mul_f32 v[158:159], v[26:27], s[100:101]
	v_exp_f32_e32 v156, v156
	v_exp_f32_e32 v157, v157
	v_exp_f32_e32 v158, v158
	v_exp_f32_e32 v159, v159
	v_pk_add_f32 v[156:157], v[156:157], 1.0 op_sel_hi:[1,0]
	v_pk_add_f32 v[158:159], v[158:159], 1.0 op_sel_hi:[1,0]
	v_rcp_f32_e32 v24, v156
	v_rcp_f32_e32 v25, v157
	v_rcp_f32_e32 v26, v158
	v_rcp_f32_e32 v27, v159
	v_pk_mul_f32 v[156:157], v[28:29], s[100:101]
	v_pk_mul_f32 v[158:159], v[30:31], s[100:101]
	v_exp_f32_e32 v156, v156
	v_exp_f32_e32 v157, v157
	v_exp_f32_e32 v158, v158
	v_exp_f32_e32 v159, v159
	v_pk_add_f32 v[156:157], v[156:157], 1.0 op_sel_hi:[1,0]
	v_pk_add_f32 v[158:159], v[158:159], 1.0 op_sel_hi:[1,0]
	v_rcp_f32_e32 v28, v156
	v_rcp_f32_e32 v29, v157
	v_rcp_f32_e32 v30, v158
	v_rcp_f32_e32 v31, v159
	s_nop 0
; __device__ __forceinline__ unsigned cvt_pk_bf16(float lo, float hi) { unsigned r; asm volatile("v_cvt_pk_bf16_f32 %0, %1, %2" : "=v"(r) : "v"(lo), "v"(hi)); return r; }
; __device__ __forceinline__ float sigmoidf_(float v) { return __builtin_amdgcn_rcpf(1.0f + __builtin_amdgcn_exp2f(-1.4426950408889634f * v)); }
;     __device__ __forceinline__ void operator()(const f32x4 (&acc)[2][2][4][2], const Unit& u, int wr, int wc, int fr, int fq) const {
;     ...
;             for (int m = 0; m < 4; ++m) {
;                 const int row = row0 + ai * HALF + m * 16;
;                 const float r = __builtin_amdgcn_rsqf(rs[ai][m] * (1.0f / DM) + EPSN);
; #pragma unroll
;                 for (int bj = 0; bj < 2; ++bj) {
;                     f32x4 v0 = acc[ai][bj][m][0] * r, v1 = acc[ai][bj][m][1] * r;
;                     if (sig) {
; #pragma unroll
;                         for (int i = 0; i < 4; ++i) { v0[i] = sigmoidf_(v0[i]); v1[i] = sigmoidf_(v1[i]); }
;                     }
;                     u32x4 w; w.x = cvt_pk_bf16(v0[0], v0[1]); w.y = cvt_pk_bf16(v0[2], v0[3]); w.z = cvt_pk_bf16(v1[0], v1[1]); w.w = cvt_pk_bf16(v1[2], v1[3]);
;                     *(u32x4*)(z + (size_t)row * DIN + col0 + bj * HALF) = w;
;                 }
.LBB0_645:
	v_add_u32_e32 v34, 0xa0, v132
	v_cvt_pk_bf16_f32 v28, v28, v29
	v_cvt_pk_bf16_f32 v29, v30, v31
	v_cvt_pk_bf16_f32 v30, v24, v25
	v_mov_b64_e32 v[24:25], s[4:5]
	v_mov_b32_e32 v33, v32
	v_cvt_pk_bf16_f32 v31, v26, v27
	v_mad_i64_i32 v[24:25], s[36:37], v34, s52, v[24:25]
	v_mov_b32_e32 v26, v32
	v_mov_b32_e32 v27, v32
	v_lshl_add_u64 v[24:25], v[120:121], 1, v[24:25]
	v_pk_mul_f32 v[22:23], v[22:23], v[26:27]
	v_pk_mul_f32 v[20:21], v[20:21], v[32:33]
	v_pk_mul_f32 v[18:19], v[18:19], v[26:27]
	s_and_b64 vcc, exec, s[0:1]
	v_pk_mul_f32 v[16:17], v[16:17], v[32:33]
	global_store_dwordx4 v[24:25], v[28:31], off
	s_cbranch_vccnz .LBB0_647
	v_pk_mul_f32 v[156:157], v[16:17], s[100:101]
	v_pk_mul_f32 v[158:159], v[18:19], s[100:101]
	v_exp_f32_e32 v156, v156
	v_exp_f32_e32 v157, v157
	v_exp_f32_e32 v158, v158
	v_exp_f32_e32 v159, v159
	v_pk_add_f32 v[156:157], v[156:157], 1.0 op_sel_hi:[1,0]
	v_pk_add_f32 v[158:159], v[158:159], 1.0 op_sel_hi:[1,0]
	v_rcp_f32_e32 v16, v156
	v_rcp_f32_e32 v17, v157
	v_rcp_f32_e32 v18, v158
	v_rcp_f32_e32 v19, v159
	v_pk_mul_f32 v[156:157], v[20:21], s[100:101]
	v_pk_mul_f32 v[158:159], v[22:23], s[100:101]
	v_exp_f32_e32 v156, v156
	v_exp_f32_e32 v157, v157
	v_exp_f32_e32 v158, v158
	v_exp_f32_e32 v159, v159
	v_pk_add_f32 v[156:157], v[156:157], 1.0 op_sel_hi:[1,0]
	v_pk_add_f32 v[158:159], v[158:159], 1.0 op_sel_hi:[1,0]
	v_rcp_f32_e32 v20, v156
	v_rcp_f32_e32 v21, v157
	v_rcp_f32_e32 v22, v158
	v_rcp_f32_e32 v23, v159
	s_nop 0
.LBB0_647:
	v_cvt_pk_bf16_f32 v20, v20, v21
	v_cvt_pk_bf16_f32 v21, v22, v23
	v_cvt_pk_bf16_f32 v22, v16, v17
	v_cvt_pk_bf16_f32 v23, v18, v19
	global_store_dwordx4 v[24:25], v[20:23], off offset:256
	v_fmamk_f32 v16, v133, 0x3a000000, v150
	v_rsq_f32_e32 v16, v16
	s_and_b64 vcc, exec, s[0:1]
	v_pk_mul_f32 v[14:15], v[14:15], v[16:17] op_sel_hi:[1,0]
	v_pk_mul_f32 v[12:13], v[12:13], v[16:17] op_sel_hi:[1,0]
	v_pk_mul_f32 v[10:11], v[10:11], v[16:17] op_sel_hi:[1,0]
	v_pk_mul_f32 v[8:9], v[8:9], v[16:17] op_sel_hi:[1,0]
	s_cbranch_vccnz .LBB0_649
	v_pk_mul_f32 v[156:157], v[8:9], s[100:101]
	v_pk_mul_f32 v[158:159], v[10:11], s[100:101]
	v_exp_f32_e32 v156, v156
	v_exp_f32_e32 v157, v157
	v_exp_f32_e32 v158, v158
	v_exp_f32_e32 v159, v159
	v_pk_add_f32 v[156:157], v[156:157], 1.0 op_sel_hi:[1,0]
	v_pk_add_f32 v[158:159], v[158:159], 1.0 op_sel_hi:[1,0]
	v_rcp_f32_e32 v8, v156
	v_rcp_f32_e32 v9, v157
	v_rcp_f32_e32 v10, v158
	v_rcp_f32_e32 v11, v159
	v_pk_mul_f32 v[156:157], v[12:13], s[100:101]
	v_pk_mul_f32 v[158:159], v[14:15], s[100:101]
	v_exp_f32_e32 v156, v156
	v_exp_f32_e32 v157, v157
	v_exp_f32_e32 v158, v158
	v_exp_f32_e32 v159, v159
	v_pk_add_f32 v[156:157], v[156:157], 1.0 op_sel_hi:[1,0]
	v_pk_add_f32 v[158:159], v[158:159], 1.0 op_sel_hi:[1,0]
	v_rcp_f32_e32 v12, v156
	v_rcp_f32_e32 v13, v157
	v_rcp_f32_e32 v14, v158
	v_rcp_f32_e32 v15, v159
	s_nop 0
.LBB0_649:
	v_add_u32_e32 v18, 0xb0, v132
	v_cvt_pk_bf16_f32 v12, v12, v13
	v_cvt_pk_bf16_f32 v13, v14, v15
	v_cvt_pk_bf16_f32 v14, v8, v9
	v_mov_b64_e32 v[8:9], s[4:5]
	v_mov_b32_e32 v17, v16
	v_cvt_pk_bf16_f32 v15, v10, v11
	v_mad_i64_i32 v[8:9], s[36:37], v18, s52, v[8:9]
	v_mov_b32_e32 v10, v16
	v_mov_b32_e32 v11, v16
	v_lshl_add_u64 v[8:9], v[120:121], 1, v[8:9]
	v_pk_mul_f32 v[6:7], v[6:7], v[10:11]
	v_pk_mul_f32 v[4:5], v[4:5], v[16:17]
	v_pk_mul_f32 v[2:3], v[2:3], v[10:11]
	s_and_b64 vcc, exec, s[0:1]
	v_pk_mul_f32 v[0:1], v[0:1], v[16:17]
	global_store_dwordx4 v[8:9], v[12:15], off
	s_cbranch_vccnz .LBB0_651
	v_pk_mul_f32 v[156:157], v[0:1], s[100:101]
	v_pk_mul_f32 v[158:159], v[2:3], s[100:101]
	v_exp_f32_e32 v156, v156
	v_exp_f32_e32 v157, v157
	v_exp_f32_e32 v158, v158
	v_exp_f32_e32 v159, v159
	v_pk_add_f32 v[156:157], v[156:157], 1.0 op_sel_hi:[1,0]
	v_pk_add_f32 v[158:159], v[158:159], 1.0 op_sel_hi:[1,0]
	v_rcp_f32_e32 v0, v156
	v_rcp_f32_e32 v1, v157
	v_rcp_f32_e32 v2, v158
	v_rcp_f32_e32 v3, v159
	v_pk_mul_f32 v[156:157], v[4:5], s[100:101]
	v_pk_mul_f32 v[158:159], v[6:7], s[100:101]
	v_exp_f32_e32 v156, v156
	v_exp_f32_e32 v157, v157
	v_exp_f32_e32 v158, v158
	v_exp_f32_e32 v159, v159
	v_pk_add_f32 v[156:157], v[156:157], 1.0 op_sel_hi:[1,0]
	v_pk_add_f32 v[158:159], v[158:159], 1.0 op_sel_hi:[1,0]
	v_rcp_f32_e32 v4, v156
	v_rcp_f32_e32 v5, v157
	v_rcp_f32_e32 v6, v158
	v_rcp_f32_e32 v7, v159
	s_nop 0
